# G1-even V tiles: column pass rewritten with in-wave transpose; F2 epilogue in coalesced mapping
# speedup vs baseline: 1.0522x; 1.0129x over previous
.LBB0_61:
	s_add_i32 s24, s46, -1
	s_min_u32 s24, s24, s45
	s_lshl_b32 s25, s24, 7
	ds_read_b128 v[178:181], v130
	ds_read_b128 v[182:185], v130 offset:32
	ds_read_b128 v[186:189], v130 offset:4608
	ds_read_b128 v[190:193], v130 offset:4640
	ds_read_b128 v[194:197], v131 offset:36864
	ds_read_b128 v[198:201], v131 offset:36896
	ds_read_b128 v[202:205], v131 offset:41472
	ds_read_b128 v[206:209], v131 offset:41504
	s_waitcnt vmcnt(15)
	ds_write_b128 v138, v[94:97] offset:18432
	buffer_load_dwordx4 v[94:97], v140, s[40:43], s25 offen
	s_waitcnt lgkmcnt(4)
	v_mfma_f32_32x32x16_bf16 v[50:65], v[178:181], v[194:197], v[50:65]
	v_mov_b32_e32 v143, s20
	s_lshl_b32 s34, s24, 6
	v_sub_co_u32_e32 v144, vcc, s34, v143
	s_add_u32 s35, s44, s25
	v_readfirstlane_b32 s96, v144
	s_addc_u32 s51, s1, 0
	s_waitcnt lgkmcnt(2)
	v_mfma_f32_32x32x16_bf16 v[34:49], v[178:181], v[202:205], v[34:49]
	s_lshl_b64 s[24:25], s[96:97], 1
	s_add_u32 s54, s21, s24
	s_addc_u32 s55, s39, s25
	s_and_b64 s[24:25], vcc, exec
	s_cselect_b32 s25, s51, s55
	s_cselect_b32 s24, s35, s54
	s_and_b32 s25, s25, 0xffff
	s_waitcnt vmcnt(15)
	ds_write_b128 v138, v[90:93] offset:55296
	buffer_load_dwordx4 v[90:93], v139, s[24:27], 0 offen
	v_mfma_f32_32x32x16_bf16 v[18:33], v[186:189], v[194:197], v[18:33]
	v_mfma_f32_32x32x16_bf16 v[2:17], v[186:189], v[202:205], v[2:17]
	s_add_i32 s34, s34, s47
	s_lshl_b32 s35, s34, 1
	ds_read_b128 v[178:181], v130 offset:64
	ds_read_b128 v[186:189], v130 offset:4672
	ds_read_b128 v[194:197], v131 offset:36928
	ds_read_b128 v[202:205], v131 offset:41536
	s_waitcnt vmcnt(15)
	ds_write_b128 v138, v[86:89] offset:23040
	buffer_load_dwordx4 v[86:89], v140, s[40:43], s35 offen
	v_mfma_f32_32x32x16_bf16 v[50:65], v[182:185], v[198:201], v[50:65]
	s_waitcnt lgkmcnt(7)
	v_mfma_f32_32x32x16_bf16 v[34:49], v[182:185], v[206:209], v[34:49]
	s_waitcnt vmcnt(15)
	ds_write_b128 v138, v[82:85] offset:59904
	buffer_load_dwordx4 v[82:85], v139, s[24:27], s94 offen
	v_mfma_f32_32x32x16_bf16 v[18:33], v[190:193], v[198:201], v[18:33]
	v_mfma_f32_32x32x16_bf16 v[2:17], v[190:193], v[206:209], v[2:17]
	s_add_i32 s34, s34, s47
	s_lshl_b32 s35, s34, 1
	ds_read_b128 v[182:185], v130 offset:96
	ds_read_b128 v[190:193], v130 offset:4704
	ds_read_b128 v[198:201], v131 offset:36960
	ds_read_b128 v[206:209], v131 offset:41568
	s_waitcnt vmcnt(15)
	ds_write_b128 v138, v[78:81] offset:27648
	buffer_load_dwordx4 v[78:81], v140, s[40:43], s35 offen
	s_waitcnt lgkmcnt(8)
	v_mfma_f32_32x32x16_bf16 v[50:65], v[178:181], v[194:197], v[50:65]
	s_waitcnt lgkmcnt(7)
	v_mfma_f32_32x32x16_bf16 v[34:49], v[178:181], v[202:205], v[34:49]
	s_waitcnt vmcnt(15)
	ds_write_b128 v138, v[74:77] offset:64512
	buffer_load_dwordx4 v[74:77], v139, s[24:27], s92 offen
	v_mfma_f32_32x32x16_bf16 v[18:33], v[186:189], v[194:197], v[18:33]
	v_mfma_f32_32x32x16_bf16 v[2:17], v[186:189], v[202:205], v[2:17]
	s_add_i32 s34, s34, s47
	s_lshl_b32 s34, s34, 1
	s_waitcnt vmcnt(15)
	ds_write_b128 v138, v[70:73] offset:32256
	buffer_load_dwordx4 v[70:73], v140, s[40:43], s34 offen
	s_waitcnt lgkmcnt(4)
	v_mfma_f32_32x32x16_bf16 v[50:65], v[182:185], v[198:201], v[50:65]
	s_waitcnt lgkmcnt(3)
	v_mfma_f32_32x32x16_bf16 v[34:49], v[182:185], v[206:209], v[34:49]
	s_waitcnt vmcnt(15)
	ds_write_b128 v142, v[66:69] offset:13824
	buffer_load_dwordx4 v[66:69], v139, s[24:27], s28 offen
	v_mfma_f32_32x32x16_bf16 v[18:33], v[190:193], v[198:201], v[18:33]
	v_mfma_f32_32x32x16_bf16 v[2:17], v[190:193], v[206:209], v[2:17]
	s_min_u32 s24, s46, s45
	s_lshl_b32 s25, s24, 7
	s_waitcnt lgkmcnt(0)
	s_barrier
	ds_read_b128 v[178:181], v130 offset:18432
	ds_read_b128 v[182:185], v130 offset:18464
	ds_read_b128 v[186:189], v130 offset:23040
	ds_read_b128 v[190:193], v130 offset:23072
	ds_read_b128 v[194:197], v131 offset:55296
	ds_read_b128 v[198:201], v131 offset:55328
	ds_read_b128 v[202:205], v131 offset:59904
	ds_read_b128 v[206:209], v131 offset:59936
	s_waitcnt vmcnt(15)
	ds_write_b128 v138, v[98:101]
	buffer_load_dwordx4 v[98:101], v140, s[40:43], s25 offen
	s_waitcnt lgkmcnt(4)
	v_mfma_f32_32x32x16_bf16 v[50:65], v[178:181], v[194:197], v[50:65]
	s_lshl_b32 s34, s24, 6
	v_sub_co_u32_e32 v143, vcc, s34, v143
	s_add_u32 s35, s44, s25
	v_readfirstlane_b32 s96, v143
	s_addc_u32 s51, s1, 0
	s_lshl_b64 s[24:25], s[96:97], 1
	s_waitcnt lgkmcnt(2)
	v_mfma_f32_32x32x16_bf16 v[34:49], v[178:181], v[202:205], v[34:49]
	s_add_u32 s54, s21, s24
	s_addc_u32 s55, s39, s25
	s_and_b64 s[24:25], vcc, exec
	s_cselect_b32 s25, s51, s55
	s_cselect_b32 s24, s35, s54
	s_and_b32 s25, s25, 0xffff
	s_waitcnt vmcnt(15)
	ds_write_b128 v138, v[102:105] offset:36864
	buffer_load_dwordx4 v[102:105], v139, s[24:27], 0 offen
	v_mfma_f32_32x32x16_bf16 v[18:33], v[186:189], v[194:197], v[18:33]
	v_mfma_f32_32x32x16_bf16 v[2:17], v[186:189], v[202:205], v[2:17]
	s_add_i32 s34, s34, s47
	s_lshl_b32 s35, s34, 1
	ds_read_b128 v[178:181], v130 offset:18496
	ds_read_b128 v[186:189], v130 offset:23104
	ds_read_b128 v[194:197], v131 offset:55360
	ds_read_b128 v[202:205], v131 offset:59968
	s_waitcnt vmcnt(15)
	ds_write_b128 v138, v[110:113] offset:4608
	buffer_load_dwordx4 v[110:113], v140, s[40:43], s35 offen
	v_mfma_f32_32x32x16_bf16 v[50:65], v[182:185], v[198:201], v[50:65]
	s_waitcnt lgkmcnt(7)
	v_mfma_f32_32x32x16_bf16 v[34:49], v[182:185], v[206:209], v[34:49]
	s_waitcnt vmcnt(15)
	ds_write_b128 v138, v[106:109] offset:41472
	buffer_load_dwordx4 v[106:109], v139, s[24:27], s94 offen
	v_mfma_f32_32x32x16_bf16 v[18:33], v[190:193], v[198:201], v[18:33]
	v_mfma_f32_32x32x16_bf16 v[2:17], v[190:193], v[206:209], v[2:17]
	s_add_i32 s34, s34, s47
	s_lshl_b32 s35, s34, 1
	ds_read_b128 v[182:185], v130 offset:18528
	ds_read_b128 v[190:193], v130 offset:23136
	ds_read_b128 v[198:201], v131 offset:55392
	ds_read_b128 v[206:209], v131 offset:60000
	s_waitcnt vmcnt(15)
	ds_write_b128 v138, v[118:121] offset:9216
	buffer_load_dwordx4 v[118:121], v140, s[40:43], s35 offen
	s_waitcnt lgkmcnt(8)
	v_mfma_f32_32x32x16_bf16 v[50:65], v[178:181], v[194:197], v[50:65]
	s_waitcnt lgkmcnt(7)
	v_mfma_f32_32x32x16_bf16 v[34:49], v[178:181], v[202:205], v[34:49]
	s_waitcnt vmcnt(15)
	ds_write_b128 v138, v[114:117] offset:46080
	buffer_load_dwordx4 v[114:117], v139, s[24:27], s92 offen
	v_mfma_f32_32x32x16_bf16 v[18:33], v[186:189], v[194:197], v[18:33]
	v_mfma_f32_32x32x16_bf16 v[2:17], v[186:189], v[202:205], v[2:17]
	s_add_i32 s34, s34, s47
	s_lshl_b32 s34, s34, 1
	s_waitcnt vmcnt(15)
	ds_write_b128 v138, v[122:125] offset:13824
	buffer_load_dwordx4 v[122:125], v140, s[40:43], s34 offen
	s_waitcnt lgkmcnt(4)
	v_mfma_f32_32x32x16_bf16 v[50:65], v[182:185], v[198:201], v[50:65]
	s_waitcnt lgkmcnt(3)
	v_mfma_f32_32x32x16_bf16 v[34:49], v[182:185], v[206:209], v[34:49]
	s_waitcnt vmcnt(15)
	ds_write_b128 v138, v[126:129] offset:50688
	buffer_load_dwordx4 v[126:129], v139, s[24:27], s28 offen
	v_mfma_f32_32x32x16_bf16 v[18:33], v[190:193], v[198:201], v[18:33]
	v_mfma_f32_32x32x16_bf16 v[2:17], v[190:193], v[206:209], v[2:17]
	s_add_i32 s24, s46, 2
	s_cmp_lt_u32 s46, s49
	s_mov_b32 s46, s24
	s_waitcnt lgkmcnt(0)
	s_barrier
	s_cbranch_scc1 .LBB0_61
	s_waitcnt vmcnt(7)
	ds_read_b128 v[98:101], v130
	s_waitcnt vmcnt(6)
	ds_read_b128 v[102:105], v131 offset:36864
	s_waitcnt vmcnt(4)
	ds_read_b128 v[106:109], v130 offset:32
	ds_read_b128 v[110:113], v131 offset:36896
	s_waitcnt vmcnt(2)
	ds_read_b128 v[114:117], v131 offset:41472
	ds_read_b128 v[118:121], v130 offset:4608
	s_waitcnt vmcnt(1)
	ds_read_b128 v[122:125], v130 offset:4640
	s_waitcnt vmcnt(0)
	ds_read_b128 v[126:129], v131 offset:41504
	ds_write_b128 v138, v[94:97] offset:18432
	s_waitcnt lgkmcnt(7)
	v_mfma_f32_32x32x16_bf16 v[50:65], v[98:101], v[102:105], v[50:65]
	s_waitcnt lgkmcnt(4)
	v_mfma_f32_32x32x16_bf16 v[34:49], v[98:101], v[114:117], v[34:49]
	s_waitcnt lgkmcnt(3)
	v_mfma_f32_32x32x16_bf16 v[18:33], v[118:121], v[102:105], v[18:33]
	ds_write_b128 v138, v[90:93] offset:55296
	v_mfma_f32_32x32x16_bf16 v[2:17], v[118:121], v[114:117], v[2:17]
	ds_read_b128 v[90:93], v130 offset:64
	ds_read_b128 v[94:97], v130 offset:4672
	ds_read_b128 v[98:101], v131 offset:36928
	ds_read_b128 v[102:105], v131 offset:41536
	v_mfma_f32_32x32x16_bf16 v[50:65], v[106:109], v[110:113], v[50:65]
	ds_write_b128 v138, v[86:89] offset:23040
	s_waitcnt lgkmcnt(7)
	v_mfma_f32_32x32x16_bf16 v[34:49], v[106:109], v[126:129], v[34:49]
	v_mfma_f32_32x32x16_bf16 v[18:33], v[122:125], v[110:113], v[18:33]
	ds_write_b128 v138, v[82:85] offset:59904
	v_mfma_f32_32x32x16_bf16 v[2:17], v[122:125], v[126:129], v[2:17]
	ds_read_b128 v[82:85], v130 offset:96
	ds_read_b128 v[86:89], v130 offset:4704
	ds_read_b128 v[106:109], v131 offset:36960
	ds_read_b128 v[110:113], v131 offset:41568
	s_waitcnt lgkmcnt(7)
	v_mfma_f32_32x32x16_bf16 v[50:65], v[90:93], v[98:101], v[50:65]
	ds_write_b128 v138, v[78:81] offset:27648
	s_waitcnt lgkmcnt(7)
	v_mfma_f32_32x32x16_bf16 v[34:49], v[90:93], v[102:105], v[34:49]
	v_mfma_f32_32x32x16_bf16 v[18:33], v[94:97], v[98:101], v[18:33]
	ds_write_b128 v138, v[74:77] offset:64512
	v_mfma_f32_32x32x16_bf16 v[2:17], v[94:97], v[102:105], v[2:17]
	s_waitcnt lgkmcnt(3)
	v_mfma_f32_32x32x16_bf16 v[50:65], v[82:85], v[106:109], v[50:65]
	ds_write_b128 v138, v[70:73] offset:32256
	s_waitcnt lgkmcnt(3)
	v_mfma_f32_32x32x16_bf16 v[34:49], v[82:85], v[110:113], v[34:49]
	v_mfma_f32_32x32x16_bf16 v[18:33], v[86:89], v[106:109], v[18:33]
	ds_write_b128 v142, v[66:69] offset:13824
	v_mfma_f32_32x32x16_bf16 v[2:17], v[86:89], v[110:113], v[2:17]
	s_waitcnt lgkmcnt(0)
	s_barrier
	ds_read_b128 v[66:69], v130 offset:18432
	ds_read_b128 v[70:73], v131 offset:55296
	ds_read_b128 v[74:77], v130 offset:18464
	ds_read_b128 v[78:81], v131 offset:55328
	ds_read_b128 v[82:85], v131 offset:59904
	ds_read_b128 v[86:89], v130 offset:23040
	ds_read_b128 v[90:93], v130 offset:23072
	ds_read_b128 v[94:97], v131 offset:59936
	s_waitcnt lgkmcnt(6)
	v_mfma_f32_32x32x16_bf16 v[50:65], v[66:69], v[70:73], v[50:65]
	s_waitcnt lgkmcnt(3)
	v_mfma_f32_32x32x16_bf16 v[34:49], v[66:69], v[82:85], v[34:49]
	s_waitcnt lgkmcnt(2)
	v_mfma_f32_32x32x16_bf16 v[18:33], v[86:89], v[70:73], v[18:33]
	v_mfma_f32_32x32x16_bf16 v[2:17], v[86:89], v[82:85], v[2:17]
	ds_read_b128 v[66:69], v130 offset:18496
	ds_read_b128 v[70:73], v130 offset:23104
	ds_read_b128 v[82:85], v131 offset:55360
	ds_read_b128 v[86:89], v131 offset:59968
	v_mfma_f32_32x32x16_bf16 v[50:65], v[74:77], v[78:81], v[50:65]
	s_waitcnt lgkmcnt(4)
	v_mfma_f32_32x32x16_bf16 v[34:49], v[74:77], v[94:97], v[34:49]
	v_mfma_f32_32x32x16_bf16 v[18:33], v[90:93], v[78:81], v[18:33]
	v_mfma_f32_32x32x16_bf16 v[2:17], v[90:93], v[94:97], v[2:17]
	ds_read_b128 v[74:77], v130 offset:18528
	ds_read_b128 v[78:81], v130 offset:23136
	ds_read_b128 v[90:93], v131 offset:55392
	ds_read_b128 v[94:97], v131 offset:60000
	s_waitcnt lgkmcnt(5)
	v_mfma_f32_32x32x16_bf16 v[50:65], v[66:69], v[82:85], v[50:65]
	s_waitcnt lgkmcnt(4)
	v_mfma_f32_32x32x16_bf16 v[34:49], v[66:69], v[86:89], v[34:49]
	v_mfma_f32_32x32x16_bf16 v[18:33], v[70:73], v[82:85], v[18:33]
	v_mfma_f32_32x32x16_bf16 v[2:17], v[70:73], v[86:89], v[2:17]
	s_waitcnt lgkmcnt(1)
	v_mfma_f32_32x32x16_bf16 v[50:65], v[74:77], v[90:93], v[50:65]
	s_waitcnt lgkmcnt(0)
	v_mfma_f32_32x32x16_bf16 v[34:49], v[74:77], v[94:97], v[34:49]
	v_mfma_f32_32x32x16_bf16 v[18:33], v[78:81], v[90:93], v[18:33]
	v_mfma_f32_32x32x16_bf16 v[2:17], v[78:81], v[94:97], v[2:17]
	v_lshl_or_b32 v66, v137, 2, v141
	s_movk_i32 s1, 0x210
	v_and_or_b32 v67, v135, 64, v136
	v_mul_lo_u32 v66, v66, s1
	v_lshl_add_u32 v66, v67, 2, v66
	s_barrier
	s_nop 3
	ds_write2_b32 v66, v50, v34 offset1:32
	ds_write2_b32 v66, v51, v35 offset0:132 offset1:164
	v_add_u32_e32 v34, 0x400, v66
	ds_write2_b32 v34, v52, v36 offset0:8 offset1:40
	ds_write2_b32 v34, v53, v37 offset0:140 offset1:172
	v_add_u32_e32 v34, 0x1000, v66
	ds_write2_b32 v34, v54, v38 offset0:32 offset1:64
	ds_write2_b32 v34, v55, v39 offset0:164 offset1:196
	v_add_u32_e32 v34, 0x1400, v66
	ds_write2_b32 v34, v56, v40 offset0:40 offset1:72
	ds_write2_b32 v34, v57, v41 offset0:172 offset1:204
	v_add_u32_e32 v34, 0x2000, v66
	ds_write2_b32 v34, v58, v42 offset0:64 offset1:96
	ds_write2_b32 v34, v59, v43 offset0:196 offset1:228
	v_add_u32_e32 v34, 0x2400, v66
	ds_write2_b32 v34, v60, v44 offset0:72 offset1:104
	ds_write2_b32 v34, v61, v45 offset0:204 offset1:236
	v_add_u32_e32 v34, 0x3000, v66
	ds_write2_b32 v34, v62, v46 offset0:96 offset1:128
	v_add_u32_e32 v34, 0x3200, v66
	ds_write2_b32 v34, v63, v47 offset0:100 offset1:132
	v_add_u32_e32 v34, 0x3400, v66
	ds_write2_b32 v34, v64, v48 offset0:104 offset1:136
	v_add_u32_e32 v34, 0x3600, v66
	ds_write2_b32 v34, v65, v49 offset0:108 offset1:140
	v_add_u32_e32 v34, 0x4000, v66
	ds_write2_b32 v34, v18, v2 offset0:128 offset1:160
	v_add_u32_e32 v2, 0x4400, v66
	ds_write2_b32 v2, v19, v3 offset0:4 offset1:36
	ds_write2_b32 v2, v20, v4 offset0:136 offset1:168
	v_add_u32_e32 v2, 0x4800, v66
	ds_write2_b32 v2, v21, v5 offset0:12 offset1:44
	v_add_u32_e32 v2, 0x5000, v66
	ds_write2_b32 v2, v22, v6 offset0:160 offset1:192
	v_add_u32_e32 v2, 0x5400, v66
	ds_write2_b32 v2, v23, v7 offset0:36 offset1:68
	ds_write2_b32 v2, v24, v8 offset0:168 offset1:200
	v_add_u32_e32 v2, 0x5800, v66
	ds_write2_b32 v2, v25, v9 offset0:44 offset1:76
	v_add_u32_e32 v2, 0x6000, v66
	ds_write2_b32 v2, v26, v10 offset0:192 offset1:224
	v_add_u32_e32 v2, 0x6400, v66
	ds_write2_b32 v2, v27, v11 offset0:68 offset1:100
	ds_write2_b32 v2, v28, v12 offset0:200 offset1:232
	v_add_u32_e32 v2, 0x6800, v66
	ds_write2_b32 v2, v29, v13 offset0:76 offset1:108
	v_add_u32_e32 v2, 0x7200, v66
	ds_write2_b32 v2, v30, v14 offset0:96 offset1:128
	v_add_u32_e32 v2, 0x7400, v66
	s_add_i32 s0, s0, s2
	ds_write2_b32 v2, v31, v15 offset0:100 offset1:132
	v_add_u32_e32 v2, 0x7600, v66
	v_add_u32_e32 v34, s0, v132
	ds_write2_b32 v2, v32, v16 offset0:104 offset1:136
	v_add_u32_e32 v2, 0x7800, v66
	v_ashrrev_i32_e32 v35, 31, v34
	v_readlane_b32 s0, v247, 9
	ds_write2_b32 v2, v33, v17 offset0:108 offset1:140
	v_lshlrev_b64 v[2:3], 11, v[34:35]
	v_readlane_b32 s1, v247, 10
	s_lshl_b32 s96, s38, 1
	s_waitcnt lgkmcnt(0)
	v_lshl_add_u64 v[2:3], s[0:1], 0, v[2:3]
	v_lshl_add_u64 v[2:3], v[2:3], 0, s[96:97]
	v_lshl_add_u64 v[30:31], v[2:3], 0, v[146:147]
	s_barrier
	v_readfirstlane_b32 s40, v34
	v_lshrrev_b32_e32 v98, 5, v0
	v_lshrrev_b32_e32 v99, 6, v0
	v_lshlrev_b32_e32 v99, 5, v99
	v_sub_u32_e32 v99, v98, v99
	v_add_u32_e32 v99, s40, v99
	v_and_b32_e32 v100, 31, v0
	v_lshlrev_b32_e32 v101, 3, v100
	v_add_u32_e32 v101, s96, v101
	v_lshl_add_u32 v102, v99, 11, v101
	v_mul_u32_u24_e32 v103, 0x880, v99
	v_add_u32_e32 v103, v103, v101
	v_mul_u32_u24_e32 v104, 0x210, v98
	v_lshl_add_u32 v104, v100, 4, v104
	global_load_dwordx2 v[66:67], v102, s[0:1]
	v_add_u32_e32 v102, 0x4000, v102
	global_load_dwordx2 v[68:69], v102, s[0:1]
	v_add_u32_e32 v102, 0x4000, v102
	global_load_dwordx2 v[70:71], v102, s[0:1]
	v_add_u32_e32 v102, 0x4000, v102
	global_load_dwordx2 v[72:73], v102, s[0:1]
	v_add_u32_e32 v102, 0x4000, v102
	global_load_dwordx2 v[74:75], v102, s[0:1]
	v_add_u32_e32 v102, 0x4000, v102
	global_load_dwordx2 v[76:77], v102, s[0:1]
	v_add_u32_e32 v102, 0x4000, v102
	global_load_dwordx2 v[78:79], v102, s[0:1]
	v_add_u32_e32 v102, 0x4000, v102
	global_load_dwordx2 v[80:81], v102, s[0:1]
	v_add_u32_e32 v102, 0x4000, v102
	global_load_dwordx2 v[82:83], v102, s[0:1]
	v_add_u32_e32 v102, 0x4000, v102
	global_load_dwordx2 v[84:85], v102, s[0:1]
	v_add_u32_e32 v102, 0x4000, v102
	global_load_dwordx2 v[86:87], v102, s[0:1]
	v_add_u32_e32 v102, 0x4000, v102
	global_load_dwordx2 v[88:89], v102, s[0:1]
	v_add_u32_e32 v102, 0x4000, v102
	global_load_dwordx2 v[90:91], v102, s[0:1]
	v_add_u32_e32 v102, 0x4000, v102
	global_load_dwordx2 v[92:93], v102, s[0:1]
	v_add_u32_e32 v102, 0x4000, v102
	global_load_dwordx2 v[94:95], v102, s[0:1]
	v_add_u32_e32 v102, 0x4000, v102
	global_load_dwordx2 v[96:97], v102, s[0:1]
	ds_read_b128 v[2:5], v104
	ds_read_b128 v[6:9], v104 offset:4224
	ds_read_b128 v[10:13], v104 offset:8448
	ds_read_b128 v[14:17], v104 offset:12672
	ds_read_b128 v[18:21], v104 offset:16896
	ds_read_b128 v[22:25], v104 offset:21120
	ds_read_b128 v[26:29], v104 offset:25344
	ds_read_b128 v[30:33], v104 offset:29568
	ds_read_b128 v[34:37], v104 offset:33792
	ds_read_b128 v[38:41], v104 offset:38016
	ds_read_b128 v[42:45], v104 offset:42240
	ds_read_b128 v[46:49], v104 offset:46464
	ds_read_b128 v[50:53], v104 offset:50688
	ds_read_b128 v[54:57], v104 offset:54912
	ds_read_b128 v[58:61], v104 offset:59136
	ds_read_b128 v[62:65], v104 offset:63360
	s_waitcnt lgkmcnt(0)
	s_waitcnt vmcnt(15)
	v_lshlrev_b32_e32 v106, 16, v66
	v_and_b32_e32 v107, 0xffff0000, v66
	v_lshlrev_b32_e32 v108, 16, v67
	v_and_b32_e32 v109, 0xffff0000, v67
	v_pk_mul_f32 v[2:3], v[2:3], v[106:107]
	v_pk_mul_f32 v[4:5], v[4:5], v[108:109]
	v_cvt_pk_bf16_f32 v66, v2, v3
	v_cvt_pk_bf16_f32 v67, v4, v5
	s_waitcnt vmcnt(14)
	v_lshlrev_b32_e32 v106, 16, v68
	v_and_b32_e32 v107, 0xffff0000, v68
	v_lshlrev_b32_e32 v108, 16, v69
	v_and_b32_e32 v109, 0xffff0000, v69
	v_pk_mul_f32 v[6:7], v[6:7], v[106:107]
	v_pk_mul_f32 v[8:9], v[8:9], v[108:109]
	v_cvt_pk_bf16_f32 v68, v6, v7
	v_cvt_pk_bf16_f32 v69, v8, v9
	s_waitcnt vmcnt(13)
	v_lshlrev_b32_e32 v106, 16, v70
	v_and_b32_e32 v107, 0xffff0000, v70
	v_lshlrev_b32_e32 v108, 16, v71
	v_and_b32_e32 v109, 0xffff0000, v71
	v_pk_mul_f32 v[10:11], v[10:11], v[106:107]
	v_pk_mul_f32 v[12:13], v[12:13], v[108:109]
	v_cvt_pk_bf16_f32 v70, v10, v11
	v_cvt_pk_bf16_f32 v71, v12, v13
	s_waitcnt vmcnt(12)
	v_lshlrev_b32_e32 v106, 16, v72
	v_and_b32_e32 v107, 0xffff0000, v72
	v_lshlrev_b32_e32 v108, 16, v73
	v_and_b32_e32 v109, 0xffff0000, v73
	v_pk_mul_f32 v[14:15], v[14:15], v[106:107]
	v_pk_mul_f32 v[16:17], v[16:17], v[108:109]
	v_cvt_pk_bf16_f32 v72, v14, v15
	v_cvt_pk_bf16_f32 v73, v16, v17
	s_waitcnt vmcnt(11)
	v_lshlrev_b32_e32 v106, 16, v74
	v_and_b32_e32 v107, 0xffff0000, v74
	v_lshlrev_b32_e32 v108, 16, v75
	v_and_b32_e32 v109, 0xffff0000, v75
	v_pk_mul_f32 v[18:19], v[18:19], v[106:107]
	v_pk_mul_f32 v[20:21], v[20:21], v[108:109]
	v_cvt_pk_bf16_f32 v74, v18, v19
	v_cvt_pk_bf16_f32 v75, v20, v21
	s_waitcnt vmcnt(10)
	v_lshlrev_b32_e32 v106, 16, v76
	v_and_b32_e32 v107, 0xffff0000, v76
	v_lshlrev_b32_e32 v108, 16, v77
	v_and_b32_e32 v109, 0xffff0000, v77
	v_pk_mul_f32 v[22:23], v[22:23], v[106:107]
	v_pk_mul_f32 v[24:25], v[24:25], v[108:109]
	v_cvt_pk_bf16_f32 v76, v22, v23
	v_cvt_pk_bf16_f32 v77, v24, v25
	s_waitcnt vmcnt(9)
	v_lshlrev_b32_e32 v106, 16, v78
	v_and_b32_e32 v107, 0xffff0000, v78
	v_lshlrev_b32_e32 v108, 16, v79
	v_and_b32_e32 v109, 0xffff0000, v79
	v_pk_mul_f32 v[26:27], v[26:27], v[106:107]
	v_pk_mul_f32 v[28:29], v[28:29], v[108:109]
	v_cvt_pk_bf16_f32 v78, v26, v27
	v_cvt_pk_bf16_f32 v79, v28, v29
	s_waitcnt vmcnt(8)
	v_lshlrev_b32_e32 v106, 16, v80
	v_and_b32_e32 v107, 0xffff0000, v80
	v_lshlrev_b32_e32 v108, 16, v81
	v_and_b32_e32 v109, 0xffff0000, v81
	v_pk_mul_f32 v[30:31], v[30:31], v[106:107]
	v_pk_mul_f32 v[32:33], v[32:33], v[108:109]
	v_cvt_pk_bf16_f32 v80, v30, v31
	v_cvt_pk_bf16_f32 v81, v32, v33
	s_waitcnt vmcnt(7)
	v_lshlrev_b32_e32 v106, 16, v82
	v_and_b32_e32 v107, 0xffff0000, v82
	v_lshlrev_b32_e32 v108, 16, v83
	v_and_b32_e32 v109, 0xffff0000, v83
	v_pk_mul_f32 v[34:35], v[34:35], v[106:107]
	v_pk_mul_f32 v[36:37], v[36:37], v[108:109]
	v_cvt_pk_bf16_f32 v82, v34, v35
	v_cvt_pk_bf16_f32 v83, v36, v37
	s_waitcnt vmcnt(6)
	v_lshlrev_b32_e32 v106, 16, v84
	v_and_b32_e32 v107, 0xffff0000, v84
	v_lshlrev_b32_e32 v108, 16, v85
	v_and_b32_e32 v109, 0xffff0000, v85
	v_pk_mul_f32 v[38:39], v[38:39], v[106:107]
	v_pk_mul_f32 v[40:41], v[40:41], v[108:109]
	v_cvt_pk_bf16_f32 v84, v38, v39
	v_cvt_pk_bf16_f32 v85, v40, v41
	s_waitcnt vmcnt(5)
	v_lshlrev_b32_e32 v106, 16, v86
	v_and_b32_e32 v107, 0xffff0000, v86
	v_lshlrev_b32_e32 v108, 16, v87
	v_and_b32_e32 v109, 0xffff0000, v87
	v_pk_mul_f32 v[42:43], v[42:43], v[106:107]
	v_pk_mul_f32 v[44:45], v[44:45], v[108:109]
	v_cvt_pk_bf16_f32 v86, v42, v43
	v_cvt_pk_bf16_f32 v87, v44, v45
	s_waitcnt vmcnt(4)
	v_lshlrev_b32_e32 v106, 16, v88
	v_and_b32_e32 v107, 0xffff0000, v88
	v_lshlrev_b32_e32 v108, 16, v89
	v_and_b32_e32 v109, 0xffff0000, v89
	v_pk_mul_f32 v[46:47], v[46:47], v[106:107]
	v_pk_mul_f32 v[48:49], v[48:49], v[108:109]
	v_cvt_pk_bf16_f32 v88, v46, v47
	v_cvt_pk_bf16_f32 v89, v48, v49
	s_waitcnt vmcnt(3)
	v_lshlrev_b32_e32 v106, 16, v90
	v_and_b32_e32 v107, 0xffff0000, v90
	v_lshlrev_b32_e32 v108, 16, v91
	v_and_b32_e32 v109, 0xffff0000, v91
	v_pk_mul_f32 v[50:51], v[50:51], v[106:107]
	v_pk_mul_f32 v[52:53], v[52:53], v[108:109]
	v_cvt_pk_bf16_f32 v90, v50, v51
	v_cvt_pk_bf16_f32 v91, v52, v53
	s_waitcnt vmcnt(2)
	v_lshlrev_b32_e32 v106, 16, v92
	v_and_b32_e32 v107, 0xffff0000, v92
	v_lshlrev_b32_e32 v108, 16, v93
	v_and_b32_e32 v109, 0xffff0000, v93
	v_pk_mul_f32 v[54:55], v[54:55], v[106:107]
	v_pk_mul_f32 v[56:57], v[56:57], v[108:109]
	v_cvt_pk_bf16_f32 v92, v54, v55
	v_cvt_pk_bf16_f32 v93, v56, v57
	s_waitcnt vmcnt(1)
	v_lshlrev_b32_e32 v106, 16, v94
	v_and_b32_e32 v107, 0xffff0000, v94
	v_lshlrev_b32_e32 v108, 16, v95
	v_and_b32_e32 v109, 0xffff0000, v95
	v_pk_mul_f32 v[58:59], v[58:59], v[106:107]
	v_pk_mul_f32 v[60:61], v[60:61], v[108:109]
	v_cvt_pk_bf16_f32 v94, v58, v59
	v_cvt_pk_bf16_f32 v95, v60, v61
	s_waitcnt vmcnt(0)
	v_lshlrev_b32_e32 v106, 16, v96
	v_and_b32_e32 v107, 0xffff0000, v96
	v_lshlrev_b32_e32 v108, 16, v97
	v_and_b32_e32 v109, 0xffff0000, v97
	v_pk_mul_f32 v[62:63], v[62:63], v[106:107]
	v_pk_mul_f32 v[64:65], v[64:65], v[108:109]
	v_cvt_pk_bf16_f32 v96, v62, v63
	v_cvt_pk_bf16_f32 v97, v64, v65
	global_store_dwordx2 v103, v[66:67], s[12:13]
	v_add_u32_e32 v103, 0x4400, v103
	global_store_dwordx2 v103, v[68:69], s[12:13]
	v_add_u32_e32 v103, 0x4400, v103
	global_store_dwordx2 v103, v[70:71], s[12:13]
	v_add_u32_e32 v103, 0x4400, v103
	global_store_dwordx2 v103, v[72:73], s[12:13]
	v_add_u32_e32 v103, 0x4400, v103
	global_store_dwordx2 v103, v[74:75], s[12:13]
	v_add_u32_e32 v103, 0x4400, v103
	global_store_dwordx2 v103, v[76:77], s[12:13]
	v_add_u32_e32 v103, 0x4400, v103
	global_store_dwordx2 v103, v[78:79], s[12:13]
	v_add_u32_e32 v103, 0x4400, v103
	global_store_dwordx2 v103, v[80:81], s[12:13]
	v_add_u32_e32 v103, 0x4400, v103
	global_store_dwordx2 v103, v[82:83], s[12:13]
	v_add_u32_e32 v103, 0x4400, v103
	global_store_dwordx2 v103, v[84:85], s[12:13]
	v_add_u32_e32 v103, 0x4400, v103
	global_store_dwordx2 v103, v[86:87], s[12:13]
	v_add_u32_e32 v103, 0x4400, v103
	global_store_dwordx2 v103, v[88:89], s[12:13]
	v_add_u32_e32 v103, 0x4400, v103
	global_store_dwordx2 v103, v[90:91], s[12:13]
	v_add_u32_e32 v103, 0x4400, v103
	global_store_dwordx2 v103, v[92:93], s[12:13]
	v_add_u32_e32 v103, 0x4400, v103
	global_store_dwordx2 v103, v[94:95], s[12:13]
	v_add_u32_e32 v103, 0x4400, v103
	global_store_dwordx2 v103, v[96:97], s[12:13]
	s_mov_b32 s96, 0x800000
	s_branch .LBB0_46

.LBB0_192:
	s_ashr_i32 s57, s56, 31
	v_readlane_b32 s40, v248, 1
	s_lshl_b64 s[0:1], s[56:57], 2
	v_readlane_b32 s42, v248, 3
	v_readlane_b32 s50, v248, 11
	v_mov_b32_e32 v130, v0
	v_readlane_b32 s43, v248, 4
	v_readlane_b32 s51, v248, 12
	s_add_u32 s42, s50, s0
	s_movk_i32 s0, 0x7f
	s_addc_u32 s43, s51, s1
	v_cmp_lt_i32_e64 s[0:1], s0, v130
	v_readlane_b32 s48, v248, 9
	v_readlane_b32 s49, v248, 10
	v_writelane_b32 v246, s0, 26
	s_cmp_gt_i32 s59, 0
	s_waitcnt lgkmcnt(11)
	v_and_b32_e32 v2, 1, v130
	v_writelane_b32 v246, s1, 27
	s_cselect_b64 s[48:49], -1, 0
	v_readlane_b32 s0, v246, 20
	v_lshlrev_b32_e32 v141, 8, v2
	s_lshl_b32 s0, s0, 5
	v_lshlrev_b32_e32 v132, 6, v2
	v_ashrrev_i32_e32 v2, 7, v130
	s_mul_i32 s20, s59, 0x550000
	s_ashr_i32 s1, s0, 31
	v_lshlrev_b32_e32 v134, 6, v2
	s_mul_hi_i32 s2, s59, 0x550000
	s_movk_i32 s21, 0x210
	v_or_b32_e32 v4, 1, v134
	s_add_u32 s20, s14, s20
	v_ashrrev_i32_e32 v140, 1, v130
	v_and_b32_e32 v143, 0x7f, v130
	s_mov_b32 s22, 0x8400
	v_mul_lo_u32 v145, v4, s21
	v_writelane_b32 v246, s20, 22
	s_addc_u32 s2, s15, s2
	v_mul_lo_u32 v3, v140, s21
	v_sub_u32_e32 v136, 0, v134
	v_lshlrev_b32_e32 v144, 2, v143
	v_mul_lo_u32 v2, v2, s22
	v_add_u32_e32 v4, 0x210, v145
	v_add_u32_e32 v5, 0x420, v145
	s_waitcnt lgkmcnt(5)
	v_add_u32_e32 v6, 0x630, v145
	v_add_u32_e32 v7, 0x840, v145
	v_add_u32_e32 v8, 0xa50, v145
	v_add_u32_e32 v9, 0xc60, v145
	s_waitcnt lgkmcnt(1)
	v_add_u32_e32 v10, 0xe70, v145
	v_add_u32_e32 v11, 0x1080, v145
	v_add_u32_e32 v12, 0x1290, v145
	s_waitcnt lgkmcnt(0)
	v_add_u32_e32 v13, 0x14a0, v145
	v_add_u32_e32 v14, 0x16b0, v145
	v_add_u32_e32 v15, 0x18c0, v145
	v_add_u32_e32 v16, 0x1ad0, v145
	v_add_u32_e32 v17, 0x1ce0, v145
	v_add_u32_e32 v18, 0x1ef0, v145
	v_add_u32_e32 v19, 0x2100, v145
	v_add_u32_e32 v20, 0x2310, v145
	v_add_u32_e32 v21, 0x2520, v145
	v_add_u32_e32 v22, 0x2730, v145
	v_add_u32_e32 v23, 0x2940, v145
	v_add_u32_e32 v24, 0x2b50, v145
	v_add_u32_e32 v25, 0x2d60, v145
	v_add_u32_e32 v26, 0x2f70, v145
	v_add_u32_e32 v27, 0x3180, v145
	v_add_u32_e32 v28, 0x3390, v145
	v_add_u32_e32 v29, 0x35a0, v145
	v_add_u32_e32 v30, 0x37b0, v145
	v_add_u32_e32 v31, 0x39c0, v145
	v_add_u32_e32 v32, 0x3bd0, v145
	v_writelane_b32 v246, s2, 20
	s_lshl_b64 s[0:1], s[0:1], 2
	s_getreg_b32 s38, hwreg(HW_REG_XCC_ID, 0, 4)
	v_cmp_eq_u32_e64 s[36:37], 0, v130
	s_mov_b32 s50, s59
	v_mov_b32_e32 v131, v147
	v_lshl_add_u32 v133, v130, 2, v170
	v_lshl_add_u32 v142, v140, 2, v170
	v_ashrrev_i32_e32 v137, 31, v136
	v_ashrrev_i32_e32 v135, 31, v134
	v_mov_b32_e32 v201, 0
	v_add_u32_e32 v152, v3, v141
	v_writelane_b32 v246, s0, 28
	v_add_u32_e32 v153, v144, v2
	v_add_u32_e32 v177, v144, v4
	v_add_u32_e32 v178, v144, v5
	v_add_u32_e32 v179, v144, v6
	v_add_u32_e32 v180, v144, v7
	v_add_u32_e32 v181, v144, v8
	v_add_u32_e32 v182, v144, v9
	v_add_u32_e32 v183, v144, v10
	v_add_u32_e32 v184, v144, v11
	v_add_u32_e32 v185, v144, v12
	v_add_u32_e32 v186, v144, v13
	v_add_u32_e32 v187, v144, v14
	v_add_u32_e32 v188, v144, v15
	v_add_u32_e32 v189, v144, v16
	v_add_u32_e32 v190, v144, v17
	v_add_u32_e32 v191, v144, v18
	v_add_u32_e32 v192, v144, v19
	v_add_u32_e32 v193, v144, v20
	v_add_u32_e32 v194, v144, v21
	v_add_u32_e32 v195, v144, v22
	v_add_u32_e32 v196, v144, v23
	v_add_u32_e32 v197, v144, v24
	v_add_u32_e32 v198, v144, v25
	v_add_u32_e32 v199, v144, v26
	v_add_u32_e32 v200, v144, v27
	v_add_u32_e32 v202, v144, v28
	v_add_u32_e32 v203, v144, v29
	v_add_u32_e32 v204, v144, v30
	v_add_u32_e32 v205, v144, v31
	v_add_u32_e32 v206, v144, v32
	v_readlane_b32 s41, v248, 2
	v_readlane_b32 s44, v248, 5
	v_readlane_b32 s45, v248, 6
	v_readlane_b32 s46, v248, 7
	v_readlane_b32 s47, v248, 8
	v_readlane_b32 s52, v248, 13
	v_readlane_b32 s53, v248, 14
	v_readlane_b32 s54, v248, 15
	v_readlane_b32 s55, v248, 16
	v_writelane_b32 v246, s1, 29
	s_branch .LBB0_195
.LBB0_194:
.LBB0_195:
	v_readlane_b32 s34, v246, 40
	v_readlane_b32 s35, v246, 41
	s_waitcnt lgkmcnt(0)
	s_barrier
	s_add_i32 s35, s34, s35
	v_writelane_b32 v246, s35, 40
	s_and_b32 s35, s34, 7
	s_lshl_b32 s35, s35, 16
	s_lshr_b32 s0, s34, 3
	s_or_b32 s0, s0, s35
	s_cmp_lt_u32 s34, 1600
	s_cselect_b32 s0, s0, -1
	s_cmp_lt_i32 s0, 0
	s_cbranch_scc1 .LBB0_214
	s_and_b32 s1, s0, 0xffff
	s_mul_i32 s1, s1, 0xcccd
	s_lshr_b32 s1, s1, 19
	s_bfe_i32 s2, s0, 0x10010
	s_and_b32 s51, s2, 10
	s_mul_i32 s2, s1, 10
	s_sub_i32 s2, s0, s2
	s_and_b32 s2, s2, 0xffff
	s_lshr_b32 s0, s0, 10
	s_add_i32 s51, s51, s2
	s_lshl_b32 s39, s1, 9
	s_and_b32 s0, s0, 0x1fff80
	v_cndmask_b32_e64 v3, 0, 1, s[48:49]
	s_mov_b32 s34, 0x800000
	s_add_i32 s39, s39, s0
	s_lshl_b32 s96, s51, 7
	v_mov_b32_e32 v2, 0
	v_cmp_ne_u32_e64 s[40:41], 1, v3
	s_andn2_b64 vcc, exec, s[48:49]
	v_mov_b32_e32 v146, 0
	s_cbranch_vccnz .LBB0_210
	s_mov_b64 s[0:1], exec
	v_readlane_b32 s20, v246, 26
	v_readlane_b32 s21, v246, 27
	s_and_b64 s[20:21], s[0:1], s[20:21]
	s_xor_b64 s[0:1], s[20:21], s[0:1]
	s_mov_b64 exec, s[20:21]
	s_cbranch_execz .LBB0_207
	v_sub_co_u32_e32 v3, vcc, s39, v171
	s_nop 0
	v_readfirstlane_b32 s2, v3
	s_lshr_b32 s2, s2, 10
	s_add_i32 s2, s2, 1
	s_and_b64 s[20:21], vcc, exec
	s_cselect_b32 s2, 0, s2
	v_readlane_b32 s20, v246, 24
	s_add_i32 s2, s2, s20
	v_readlane_b32 s52, v248, 1
	s_mul_hi_u32 s20, s2, 0x3000
	s_mulk_i32 s2, 0x3000
	v_readlane_b32 s66, v248, 15
	v_readlane_b32 s67, v248, 16
	s_add_u32 s2, s66, s2
	s_addc_u32 s21, s67, s20
	s_lshl_b32 s20, s96, 2
	s_add_u32 s20, s2, s20
	s_addc_u32 s21, s21, 0
	v_lshl_add_u64 v[4:5], v[130:131], 2, s[20:21]
	global_load_dword v146, v[4:5], off offset:-512
	v_readlane_b32 s60, v248, 9
	v_readlane_b32 s61, v248, 10
	v_readlane_b32 s62, v248, 11
	v_readlane_b32 s63, v248, 12
	v_readlane_b32 s64, v248, 13
	v_readlane_b32 s65, v248, 14
	v_readlane_b32 s60, v248, 21
	v_readlane_b32 s53, v248, 2
	v_readlane_b32 s54, v248, 3
	v_readlane_b32 s55, v248, 4
	v_readlane_b32 s56, v248, 5
	v_readlane_b32 s57, v248, 6
	v_readlane_b32 s58, v248, 7
	v_readlane_b32 s59, v248, 8
	v_readlane_b32 s61, v248, 22
	v_readlane_b32 s62, v248, 23
	v_readlane_b32 s63, v248, 24
	v_readlane_b32 s64, v248, 25
	v_readlane_b32 s65, v248, 26
	v_readlane_b32 s66, v248, 27
	v_readlane_b32 s67, v248, 28
	v_readlane_b32 s68, v248, 29
	v_readlane_b32 s69, v248, 30
	v_readlane_b32 s70, v248, 31
	v_readlane_b32 s71, v248, 32
	v_readlane_b32 s72, v248, 33
	v_readlane_b32 s73, v248, 34
	v_readlane_b32 s74, v248, 35
	v_readlane_b32 s75, v248, 36

.LBB0_251:
	v_or_b32_e32 v2, v2, v143
	v_ashrrev_i32_e32 v3, 31, v2
	v_lshlrev_b64 v[2:3], s22, v[2:3]
	v_lshl_add_u64 v[2:3], s[20:21], 0, v[2:3]
	v_lshl_add_u64 v[2:3], v[146:147], 1, v[2:3]
	v_lshl_add_u64 v[2:3], v[136:137], 1, v[2:3]
	v_lshl_add_u64 v[100:101], v[134:135], 1, v[2:3]
	v_lshrrev_b32_e32 v110, 7, v0
	v_and_b32_e32 v111, 0x7f, v0
	s_mov_b32 s44, 0x8400
	v_mul_lo_u32 v112, v110, s44
	v_lshl_add_u32 v113, v111, 2, v112
	s_cmp_eq_u32 s54, -1
	s_cbranch_scc1 .Lvc_noaff
	v_lshl_add_u32 v114, v110, 8, s54
	v_lshl_add_u32 v115, v111, 2, s54
	ds_read_b32 v102, v115 offset:512
	ds_read_b32 v36, v113 offset:0
	ds_read_b32 v37, v113 offset:528
	ds_read_b32 v38, v113 offset:1056
	ds_read_b32 v39, v113 offset:1584
	ds_read_b32 v40, v113 offset:2112
	ds_read_b32 v41, v113 offset:2640
	ds_read_b32 v42, v113 offset:3168
	ds_read_b32 v43, v113 offset:3696
	ds_read_b128 v[68:71], v114 offset:0
	ds_read_b128 v[72:75], v114 offset:16
	ds_read_b32 v44, v113 offset:4224
	ds_read_b32 v45, v113 offset:4752
	ds_read_b32 v46, v113 offset:5280
	ds_read_b32 v47, v113 offset:5808
	ds_read_b32 v48, v113 offset:6336
	ds_read_b32 v49, v113 offset:6864
	ds_read_b32 v50, v113 offset:7392
	ds_read_b32 v51, v113 offset:7920
	ds_read_b128 v[76:79], v114 offset:32
	ds_read_b128 v[80:83], v114 offset:48
	ds_read_b32 v52, v113 offset:8448
	ds_read_b32 v53, v113 offset:8976
	ds_read_b32 v54, v113 offset:9504
	ds_read_b32 v55, v113 offset:10032
	ds_read_b32 v56, v113 offset:10560
	ds_read_b32 v57, v113 offset:11088
	ds_read_b32 v58, v113 offset:11616
	ds_read_b32 v59, v113 offset:12144
	ds_read_b128 v[84:87], v114 offset:64
	ds_read_b128 v[88:91], v114 offset:80
	ds_read_b32 v60, v113 offset:12672
	ds_read_b32 v61, v113 offset:13200
	ds_read_b32 v62, v113 offset:13728
	ds_read_b32 v63, v113 offset:14256
	ds_read_b32 v64, v113 offset:14784
	ds_read_b32 v65, v113 offset:15312
	ds_read_b32 v66, v113 offset:15840
	ds_read_b32 v67, v113 offset:16368
	ds_read_b128 v[92:95], v114 offset:96
	ds_read_b128 v[96:99], v114 offset:112
	s_waitcnt lgkmcnt(0)
	v_pk_fma_f32 v[36:37], v[36:37], v[68:69], v[102:103] op_sel_hi:[1,1,0]
	v_pk_fma_f32 v[38:39], v[38:39], v[70:71], v[102:103] op_sel_hi:[1,1,0]
	v_pk_fma_f32 v[40:41], v[40:41], v[72:73], v[102:103] op_sel_hi:[1,1,0]
	v_pk_fma_f32 v[42:43], v[42:43], v[74:75], v[102:103] op_sel_hi:[1,1,0]
	v_cvt_pk_bf16_f32 v4, v36, v37
	v_cvt_pk_bf16_f32 v5, v38, v39
	v_cvt_pk_bf16_f32 v6, v40, v41
	v_cvt_pk_bf16_f32 v7, v42, v43
	v_pk_fma_f32 v[44:45], v[44:45], v[76:77], v[102:103] op_sel_hi:[1,1,0]
	v_pk_fma_f32 v[46:47], v[46:47], v[78:79], v[102:103] op_sel_hi:[1,1,0]
	v_pk_fma_f32 v[48:49], v[48:49], v[80:81], v[102:103] op_sel_hi:[1,1,0]
	v_pk_fma_f32 v[50:51], v[50:51], v[82:83], v[102:103] op_sel_hi:[1,1,0]
	v_cvt_pk_bf16_f32 v8, v44, v45
	v_cvt_pk_bf16_f32 v9, v46, v47
	v_cvt_pk_bf16_f32 v10, v48, v49
	v_cvt_pk_bf16_f32 v11, v50, v51
	v_pk_fma_f32 v[52:53], v[52:53], v[84:85], v[102:103] op_sel_hi:[1,1,0]
	v_pk_fma_f32 v[54:55], v[54:55], v[86:87], v[102:103] op_sel_hi:[1,1,0]
	v_pk_fma_f32 v[56:57], v[56:57], v[88:89], v[102:103] op_sel_hi:[1,1,0]
	v_pk_fma_f32 v[58:59], v[58:59], v[90:91], v[102:103] op_sel_hi:[1,1,0]
	v_cvt_pk_bf16_f32 v12, v52, v53
	v_cvt_pk_bf16_f32 v13, v54, v55
	v_cvt_pk_bf16_f32 v14, v56, v57
	v_cvt_pk_bf16_f32 v15, v58, v59
	v_pk_fma_f32 v[60:61], v[60:61], v[92:93], v[102:103] op_sel_hi:[1,1,0]
	v_pk_fma_f32 v[62:63], v[62:63], v[94:95], v[102:103] op_sel_hi:[1,1,0]
	v_pk_fma_f32 v[64:65], v[64:65], v[96:97], v[102:103] op_sel_hi:[1,1,0]
	v_pk_fma_f32 v[66:67], v[66:67], v[98:99], v[102:103] op_sel_hi:[1,1,0]
	v_cvt_pk_bf16_f32 v16, v60, v61
	v_cvt_pk_bf16_f32 v17, v62, v63
	v_cvt_pk_bf16_f32 v18, v64, v65
	v_cvt_pk_bf16_f32 v19, v66, v67
	ds_read_b32 v36, v113 offset:16896
	ds_read_b32 v37, v113 offset:17424
	ds_read_b32 v38, v113 offset:17952
	ds_read_b32 v39, v113 offset:18480
	ds_read_b32 v40, v113 offset:19008
	ds_read_b32 v41, v113 offset:19536
	ds_read_b32 v42, v113 offset:20064
	ds_read_b32 v43, v113 offset:20592
	ds_read_b128 v[68:71], v114 offset:128
	ds_read_b128 v[72:75], v114 offset:144
	ds_read_b32 v44, v113 offset:21120
	ds_read_b32 v45, v113 offset:21648
	ds_read_b32 v46, v113 offset:22176
	ds_read_b32 v47, v113 offset:22704
	ds_read_b32 v48, v113 offset:23232
	ds_read_b32 v49, v113 offset:23760
	ds_read_b32 v50, v113 offset:24288
	ds_read_b32 v51, v113 offset:24816
	ds_read_b128 v[76:79], v114 offset:160
	ds_read_b128 v[80:83], v114 offset:176
	ds_read_b32 v52, v113 offset:25344
	ds_read_b32 v53, v113 offset:25872
	ds_read_b32 v54, v113 offset:26400
	ds_read_b32 v55, v113 offset:26928
	ds_read_b32 v56, v113 offset:27456
	ds_read_b32 v57, v113 offset:27984
	ds_read_b32 v58, v113 offset:28512
	ds_read_b32 v59, v113 offset:29040
	ds_read_b128 v[84:87], v114 offset:192
	ds_read_b128 v[88:91], v114 offset:208
	ds_read_b32 v60, v113 offset:29568
	ds_read_b32 v61, v113 offset:30096
	ds_read_b32 v62, v113 offset:30624
	ds_read_b32 v63, v113 offset:31152
	ds_read_b32 v64, v113 offset:31680
	ds_read_b32 v65, v113 offset:32208
	ds_read_b32 v66, v113 offset:32736
	ds_read_b32 v67, v113 offset:33264
	ds_read_b128 v[92:95], v114 offset:224
	ds_read_b128 v[96:99], v114 offset:240
	s_waitcnt lgkmcnt(0)
	v_pk_fma_f32 v[36:37], v[36:37], v[68:69], v[102:103] op_sel_hi:[1,1,0]
	v_pk_fma_f32 v[38:39], v[38:39], v[70:71], v[102:103] op_sel_hi:[1,1,0]
	v_pk_fma_f32 v[40:41], v[40:41], v[72:73], v[102:103] op_sel_hi:[1,1,0]
	v_pk_fma_f32 v[42:43], v[42:43], v[74:75], v[102:103] op_sel_hi:[1,1,0]
	v_cvt_pk_bf16_f32 v20, v36, v37
	v_cvt_pk_bf16_f32 v21, v38, v39
	v_cvt_pk_bf16_f32 v22, v40, v41
	v_cvt_pk_bf16_f32 v23, v42, v43
	v_pk_fma_f32 v[44:45], v[44:45], v[76:77], v[102:103] op_sel_hi:[1,1,0]
	v_pk_fma_f32 v[46:47], v[46:47], v[78:79], v[102:103] op_sel_hi:[1,1,0]
	v_pk_fma_f32 v[48:49], v[48:49], v[80:81], v[102:103] op_sel_hi:[1,1,0]
	v_pk_fma_f32 v[50:51], v[50:51], v[82:83], v[102:103] op_sel_hi:[1,1,0]
	v_cvt_pk_bf16_f32 v24, v44, v45
	v_cvt_pk_bf16_f32 v25, v46, v47
	v_cvt_pk_bf16_f32 v26, v48, v49
	v_cvt_pk_bf16_f32 v27, v50, v51
	v_pk_fma_f32 v[52:53], v[52:53], v[84:85], v[102:103] op_sel_hi:[1,1,0]
	v_pk_fma_f32 v[54:55], v[54:55], v[86:87], v[102:103] op_sel_hi:[1,1,0]
	v_pk_fma_f32 v[56:57], v[56:57], v[88:89], v[102:103] op_sel_hi:[1,1,0]
	v_pk_fma_f32 v[58:59], v[58:59], v[90:91], v[102:103] op_sel_hi:[1,1,0]
	v_cvt_pk_bf16_f32 v28, v52, v53
	v_cvt_pk_bf16_f32 v29, v54, v55
	v_cvt_pk_bf16_f32 v30, v56, v57
	v_cvt_pk_bf16_f32 v31, v58, v59
	v_pk_fma_f32 v[60:61], v[60:61], v[92:93], v[102:103] op_sel_hi:[1,1,0]
	v_pk_fma_f32 v[62:63], v[62:63], v[94:95], v[102:103] op_sel_hi:[1,1,0]
	v_pk_fma_f32 v[64:65], v[64:65], v[96:97], v[102:103] op_sel_hi:[1,1,0]
	v_pk_fma_f32 v[66:67], v[66:67], v[98:99], v[102:103] op_sel_hi:[1,1,0]
	v_cvt_pk_bf16_f32 v32, v60, v61
	v_cvt_pk_bf16_f32 v33, v62, v63
	v_cvt_pk_bf16_f32 v34, v64, v65
	v_cvt_pk_bf16_f32 v35, v66, v67
	s_branch .Lvc_pack_done
.Lvc_noaff:
	ds_read_b32 v36, v113 offset:0
	ds_read_b32 v37, v113 offset:528
	ds_read_b32 v38, v113 offset:1056
	ds_read_b32 v39, v113 offset:1584
	ds_read_b32 v40, v113 offset:2112
	ds_read_b32 v41, v113 offset:2640
	ds_read_b32 v42, v113 offset:3168
	ds_read_b32 v43, v113 offset:3696
	ds_read_b32 v44, v113 offset:4224
	ds_read_b32 v45, v113 offset:4752
	ds_read_b32 v46, v113 offset:5280
	ds_read_b32 v47, v113 offset:5808
	ds_read_b32 v48, v113 offset:6336
	ds_read_b32 v49, v113 offset:6864
	ds_read_b32 v50, v113 offset:7392
	ds_read_b32 v51, v113 offset:7920
	ds_read_b32 v52, v113 offset:8448
	ds_read_b32 v53, v113 offset:8976
	ds_read_b32 v54, v113 offset:9504
	ds_read_b32 v55, v113 offset:10032
	ds_read_b32 v56, v113 offset:10560
	ds_read_b32 v57, v113 offset:11088
	ds_read_b32 v58, v113 offset:11616
	ds_read_b32 v59, v113 offset:12144
	ds_read_b32 v60, v113 offset:12672
	ds_read_b32 v61, v113 offset:13200
	ds_read_b32 v62, v113 offset:13728
	ds_read_b32 v63, v113 offset:14256
	ds_read_b32 v64, v113 offset:14784
	ds_read_b32 v65, v113 offset:15312
	ds_read_b32 v66, v113 offset:15840
	ds_read_b32 v67, v113 offset:16368
	s_waitcnt lgkmcnt(0)
	v_cvt_pk_bf16_f32 v4, v36, v37
	v_cvt_pk_bf16_f32 v5, v38, v39
	v_cvt_pk_bf16_f32 v6, v40, v41
	v_cvt_pk_bf16_f32 v7, v42, v43
	v_cvt_pk_bf16_f32 v8, v44, v45
	v_cvt_pk_bf16_f32 v9, v46, v47
	v_cvt_pk_bf16_f32 v10, v48, v49
	v_cvt_pk_bf16_f32 v11, v50, v51
	v_cvt_pk_bf16_f32 v12, v52, v53
	v_cvt_pk_bf16_f32 v13, v54, v55
	v_cvt_pk_bf16_f32 v14, v56, v57
	v_cvt_pk_bf16_f32 v15, v58, v59
	v_cvt_pk_bf16_f32 v16, v60, v61
	v_cvt_pk_bf16_f32 v17, v62, v63
	v_cvt_pk_bf16_f32 v18, v64, v65
	v_cvt_pk_bf16_f32 v19, v66, v67
	ds_read_b32 v36, v113 offset:16896
	ds_read_b32 v37, v113 offset:17424
	ds_read_b32 v38, v113 offset:17952
	ds_read_b32 v39, v113 offset:18480
	ds_read_b32 v40, v113 offset:19008
	ds_read_b32 v41, v113 offset:19536
	ds_read_b32 v42, v113 offset:20064
	ds_read_b32 v43, v113 offset:20592
	ds_read_b32 v44, v113 offset:21120
	ds_read_b32 v45, v113 offset:21648
	ds_read_b32 v46, v113 offset:22176
	ds_read_b32 v47, v113 offset:22704
	ds_read_b32 v48, v113 offset:23232
	ds_read_b32 v49, v113 offset:23760
	ds_read_b32 v50, v113 offset:24288
	ds_read_b32 v51, v113 offset:24816
	ds_read_b32 v52, v113 offset:25344
	ds_read_b32 v53, v113 offset:25872
	ds_read_b32 v54, v113 offset:26400
	ds_read_b32 v55, v113 offset:26928
	ds_read_b32 v56, v113 offset:27456
	ds_read_b32 v57, v113 offset:27984
	ds_read_b32 v58, v113 offset:28512
	ds_read_b32 v59, v113 offset:29040
	ds_read_b32 v60, v113 offset:29568
	ds_read_b32 v61, v113 offset:30096
	ds_read_b32 v62, v113 offset:30624
	ds_read_b32 v63, v113 offset:31152
	ds_read_b32 v64, v113 offset:31680
	ds_read_b32 v65, v113 offset:32208
	ds_read_b32 v66, v113 offset:32736
	ds_read_b32 v67, v113 offset:33264
	s_waitcnt lgkmcnt(0)
	v_cvt_pk_bf16_f32 v20, v36, v37
	v_cvt_pk_bf16_f32 v21, v38, v39
	v_cvt_pk_bf16_f32 v22, v40, v41
	v_cvt_pk_bf16_f32 v23, v42, v43
	v_cvt_pk_bf16_f32 v24, v44, v45
	v_cvt_pk_bf16_f32 v25, v46, v47
	v_cvt_pk_bf16_f32 v26, v48, v49
	v_cvt_pk_bf16_f32 v27, v50, v51
	v_cvt_pk_bf16_f32 v28, v52, v53
	v_cvt_pk_bf16_f32 v29, v54, v55
	v_cvt_pk_bf16_f32 v30, v56, v57
	v_cvt_pk_bf16_f32 v31, v58, v59
	v_cvt_pk_bf16_f32 v32, v60, v61
	v_cvt_pk_bf16_f32 v33, v62, v63
	v_cvt_pk_bf16_f32 v34, v64, v65
	v_cvt_pk_bf16_f32 v35, v66, v67
.Lvc_pack_done:
	s_barrier
	v_and_b32_e32 v116, 63, v0
	v_lshl_add_u32 v117, v110, 6, v116
	v_mul_u32_u24_e32 v117, 0x210, v117
	v_bfe_u32 v118, v0, 6, 1
	v_lshl_add_u32 v117, v118, 8, v117
	v_add_u32_e32 v117, 0x80, v117
	ds_write_b128 v117, v[4:7]
	ds_write_b128 v117, v[8:11] offset:16
	ds_write_b128 v117, v[12:15] offset:32
	ds_write_b128 v117, v[16:19] offset:48
	ds_write_b128 v117, v[20:23] offset:64
	ds_write_b128 v117, v[24:27] offset:80
	ds_write_b128 v117, v[28:31] offset:96
	ds_write_b128 v117, v[32:35] offset:112
	v_lshrrev_b32_e32 v119, 3, v116
	v_lshl_add_u32 v120, v110, 6, v119
	v_mul_u32_u24_e32 v120, 0x210, v120
	v_lshl_add_u32 v120, v118, 8, v120
	v_and_b32_e32 v121, 7, v0
	v_lshl_add_u32 v120, v121, 4, v120
	v_add_u32_e32 v120, 0x80, v120
	v_sub_u32_e32 v122, v119, v116
	v_lshlrev_b32_e32 v122, s22, v122
	v_lshl_add_u32 v122, v121, 4, v122
	v_ashrrev_i32_e32 v123, 31, v122
	v_lshl_add_u64 v[100:101], v[100:101], 0, v[122:123]
	s_lshl_b32 s44, 8, s22
	s_mov_b32 s45, 0
	s_waitcnt lgkmcnt(0)
	ds_read_b128 v[36:39], v120
	ds_read_b128 v[40:43], v120 offset:4224
	ds_read_b128 v[44:47], v120 offset:8448
	ds_read_b128 v[48:51], v120 offset:12672
	ds_read_b128 v[52:55], v120 offset:16896
	ds_read_b128 v[56:59], v120 offset:21120
	ds_read_b128 v[60:63], v120 offset:25344
	ds_read_b128 v[64:67], v120 offset:29568
	s_waitcnt lgkmcnt(7)
	global_store_dwordx4 v[100:101], v[36:39], off
	v_lshl_add_u64 v[100:101], v[100:101], 0, s[44:45]
	s_waitcnt lgkmcnt(6)
	global_store_dwordx4 v[100:101], v[40:43], off
	v_lshl_add_u64 v[100:101], v[100:101], 0, s[44:45]
	s_waitcnt lgkmcnt(5)
	global_store_dwordx4 v[100:101], v[44:47], off
	v_lshl_add_u64 v[100:101], v[100:101], 0, s[44:45]
	s_waitcnt lgkmcnt(4)
	global_store_dwordx4 v[100:101], v[48:51], off
	v_lshl_add_u64 v[100:101], v[100:101], 0, s[44:45]
	s_waitcnt lgkmcnt(3)
	global_store_dwordx4 v[100:101], v[52:55], off
	v_lshl_add_u64 v[100:101], v[100:101], 0, s[44:45]
	s_waitcnt lgkmcnt(2)
	global_store_dwordx4 v[100:101], v[56:59], off
	v_lshl_add_u64 v[100:101], v[100:101], 0, s[44:45]
	s_waitcnt lgkmcnt(1)
	global_store_dwordx4 v[100:101], v[60:63], off
	v_lshl_add_u64 v[100:101], v[100:101], 0, s[44:45]
	s_waitcnt lgkmcnt(0)
	global_store_dwordx4 v[100:101], v[64:67], off
	s_branch .LBB0_194
